# gating: per-unit vmcnt(0) at the unit top removed (it only drained the previous unit's two MIX stores, now exposed since the end-of-unit barrier is gone)
# speedup vs baseline: 1.0195x; 1.0049x over previous
.LBB0_45:
	s_and_b32 s22, s3, 7
	s_lshl_b32 s72, s22, 8
	s_waitcnt vmcnt(23)
	v_add_f32_e32 v90, v28, v30
	v_add_f32_e32 v91, v29, v31
	s_nop 1
	v_add_f32_dpp v90, v90, v90 quad_perm:[1,0,3,2] row_mask:0xf bank_mask:0xf
	v_add_f32_dpp v91, v91, v91 quad_perm:[1,0,3,2] row_mask:0xf bank_mask:0xf
	s_nop 1
	v_add_f32_dpp v90, v90, v90 quad_perm:[2,3,0,1] row_mask:0xf bank_mask:0xf
	v_add_f32_dpp v91, v91, v91 quad_perm:[2,3,0,1] row_mask:0xf bank_mask:0xf
	s_nop 0
	s_nop 0
	v_mul_f32_e32 v115, 0x3b000000, v90
	s_lshl_b32 s19, s22, 6
	v_mul_f32_e32 v115, v115, v115
	s_mov_b32 s22, 0x3b000000
	v_fma_f32 v91, v91, s22, -v115
	v_max_f32_e32 v91, 0, v91
	v_add_f32_e32 v91, 0x358637bd, v91
	v_rsq_f32_e32 v91, v91
	s_waitcnt vmcnt(21)
	v_lshlrev_b32_e32 v92, 16, v36
	v_lshlrev_b32_e32 v94, 16, v37
	v_lshlrev_b32_e32 v96, 16, v38
	v_and_b32_e32 v93, 0xffff0000, v36
	v_and_b32_e32 v95, 0xffff0000, v37
	v_and_b32_e32 v97, 0xffff0000, v38
	v_fmac_f32_e32 v92, 0xbb000000, v90
	v_fmac_f32_e32 v94, 0xbb000000, v90
	v_fmac_f32_e32 v96, 0xbb000000, v90
	v_lshlrev_b32_e32 v98, 16, v39
	v_fmac_f32_e32 v93, 0xbb000000, v90
	v_fmac_f32_e32 v95, 0xbb000000, v90
	v_fmac_f32_e32 v97, 0xbb000000, v90
	v_mul_f32_e32 v88, v92, v91
	v_mul_f32_e32 v92, v94, v91
	v_mul_f32_e32 v94, v96, v91
	v_fmac_f32_e32 v98, 0xbb000000, v90
	v_mul_f32_e32 v89, v93, v91
	v_mul_f32_e32 v93, v95, v91
	v_mul_f32_e32 v95, v97, v91
	v_and_b32_e32 v99, 0xffff0000, v39
	v_mul_f32_e32 v96, v98, v91
	v_fmac_f32_e32 v99, 0xbb000000, v90
	v_mul_f32_e32 v97, v99, v91
	s_mov_b32 s13, s3
	v_fma_f32 v68, v88, v218, v234
	v_fma_f32 v69, v89, v219, v235
	v_fma_f32 v12, v94, v222, v238
	v_fma_f32 v70, v92, v220, v236
	v_fma_f32 v71, v93, v221, v237
	v_fma_f32 v13, v95, v223, v239
	v_fma_f32 v14, v96, v224, v240
	v_cvt_pk_bf16_f32 v180, v68, v69
	ds_write_b16 v134, v180
	ds_write_b16_d16_hi v135, v180 offset:272
	v_cvt_pk_bf16_f32 v181, v70, v71
	ds_write_b16 v134, v181 offset:544
	ds_write_b16_d16_hi v135, v181 offset:816
	v_cvt_pk_bf16_f32 v182, v12, v13
	ds_write_b16 v134, v182 offset:1088
	ds_write_b16_d16_hi v135, v182 offset:1360
	v_fma_f32 v15, v97, v225, v241
	v_cvt_pk_bf16_f32 v183, v14, v15
	ds_write_b16 v134, v183 offset:1632
	ds_write_b16_d16_hi v135, v183 offset:1904
	v_lshlrev_b32_e32 v12, 16, v32
	v_fmac_f32_e32 v12, 0xbb000000, v90
	v_mul_f32_e32 v12, v12, v91
	v_fma_f32 v4, v12, v226, v242
	v_and_b32_e32 v8, 0xffff0000, v32
	v_fmac_f32_e32 v8, 0xbb000000, v90
	v_mul_f32_e32 v8, v8, v91
	v_fma_f32 v5, v8, v227, v243
	v_cvt_pk_bf16_f32 v184, v4, v5
	ds_write_b16 v134, v184 offset:2176
	ds_write_b16_d16_hi v135, v184 offset:2448
	v_lshlrev_b32_e32 v4, 16, v33
	v_fmac_f32_e32 v4, 0xbb000000, v90
	v_and_b32_e32 v5, 0xffff0000, v33
	v_mul_f32_e32 v4, v4, v91
	v_fmac_f32_e32 v5, 0xbb000000, v90
	v_fma_f32 v4, v4, v228, v244
	v_mul_f32_e32 v5, v5, v91
	v_fma_f32 v7, v5, v229, v245
	v_cvt_pk_bf16_f32 v185, v4, v7
	ds_write_b16 v134, v185 offset:2720
	ds_write_b16_d16_hi v135, v185 offset:2992
	v_lshlrev_b32_e32 v4, 16, v34
	v_fmac_f32_e32 v4, 0xbb000000, v90
	v_mul_f32_e32 v4, v4, v91
	v_and_b32_e32 v5, 0xffff0000, v34
	v_fma_f32 v4, v4, v230, v246
	v_fmac_f32_e32 v5, 0xbb000000, v90
	v_mul_f32_e32 v5, v5, v91
	v_fma_f32 v5, v5, v231, v247
	v_cvt_pk_bf16_f32 v186, v4, v5
	ds_write_b16 v134, v186 offset:3264
	ds_write_b16_d16_hi v135, v186 offset:3536
	v_lshlrev_b32_e32 v4, 16, v35
	v_fmac_f32_e32 v4, 0xbb000000, v90
	v_and_b32_e32 v5, 0xffff0000, v35
	v_mul_f32_e32 v4, v4, v91
	v_fmac_f32_e32 v5, 0xbb000000, v90
	v_fma_f32 v4, v4, v232, v248
	v_mul_f32_e32 v5, v5, v91
	v_fma_f32 v87, v5, v233, v249
	v_cvt_pk_bf16_f32 v187, v4, v87
	ds_write_b16 v134, v187 offset:3808
	ds_write_b16_d16_hi v135, v187 offset:4080
	s_branch .LBB0_47
